# plus scan compute waves: output row addresses 1..3 derived from row 0 by a signed stride
# speedup vs baseline: 1.0030x; 1.0030x over previous
; __device__ __forceinline__ unsigned pk2n(float lo, float hi) { return __builtin_bit_cast(unsigned, __builtin_convertvector((f32x2){lo, hi}, bf16v2)); }
; __device__ __forceinline__ void scan_phase(const Params& P, int l, LAS unsigned char* lds) {
;     ...
;                     for (int j = 0; j < 4; ++j) sf[j] = __builtin_bit_cast(bf16x8, (u32x4){pk2n(St[2 * j][0], St[2 * j][1]), pk2n(St[2 * j][2], St[2 * j][3]), pk2n(St[2 * j + 1][0], St[2 * j + 1][1]), pk2n(St[2 * j + 1][2], St[2 * j + 1][3])});
;                     const bf16x8 bv = __builtin_bit_cast(bf16x8, (u32x4){pk2n(b4[0] * v4[0], b4[1] * v4[1]), pk2n(b4[2] * v4[2], b4[3] * v4[3]), 0u, 0u});
;                     const bf16x8 FT8 = __builtin_bit_cast(bf16x8, (u32x4){ft[0], ft[1], 0u, 0u}), FA8 = __builtin_bit_cast(bf16x8, (u32x4){fa[0], fa[1], 0u, 0u});
;                     const f32x4 U = __builtin_amdgcn_mfma_f32_16x16x32_bf16(FT8, bv, zero4, 0, 0, 0);
;                     f32x4 Pw = zero4, O = zero4;
; #pragma unroll
;                     for (int j = 0; j < 4; ++j) { Pw = __builtin_amdgcn_mfma_f32_16x16x32_bf16(__builtin_bit_cast(bf16x8, fw[j]), sf[j], Pw, 0, 0, 0);
;                         O = __builtin_amdgcn_mfma_f32_16x16x32_bf16(__builtin_bit_cast(bf16x8, fq[j]), sf[j], O, 0, 0, 0); }
;                     const f32x4 Vn = U - Pw;
;                     const bf16x8 vn8 = __builtin_bit_cast(bf16x8, (u32x4){pk2n(Vn[0], Vn[1]), pk2n(Vn[2], Vn[3]), 0u, 0u});
;                     O = __builtin_amdgcn_mfma_f32_16x16x32_bf16(FA8, vn8, O, 0, 0, 0);
; #pragma unroll
;                     for (int m = 0; m < 8; ++m) St[m] = __builtin_amdgcn_mfma_f32_16x16x32_bf16(__builtin_bit_cast(bf16x8, (u32x4){fk[m][0], fk[m][1], 0u, 0u}), vn8, St[m] * egC, 0, 0, 0);
; #pragma unroll
;                     for (int e = 0; e < 4; ++e) { const int t = 4 * quad + e; const int p = dir ? plo + TS - 1 - t : plo + t;
;                         Odn[(rowbase + p) * 1024 + h * 128 + col0 + col] = (bf16_t)(pk2n(O[e], 0.f) & 0xffffu); }
.LBB0_779:
	s_cmp_lt_i32 s9, 0
	s_cbranch_scc1 .LBB0_778
	s_bitcmp1_b32 s9, 0
	s_cselect_b32 s15, 0x6500, 0
	s_add_i32 s19, s15, 0
	v_add_u32_e32 v0, s19, v46
	v_add_u32_e32 v1, s19, v48
	v_add_u32_e32 v42, s19, v90
	ds_read_b128 v[38:41], v0 offset:15616
	ds_read_b128 v[60:63], v0 offset:16640
	ds_read_b128 v[64:67], v0 offset:17664
	ds_read_b128 v[68:71], v0 offset:18688
	v_add_u32_e32 v43, 0x100, v1
	ds_read_b128 v[72:75], v42 offset:24320
	ds_read_b128 v[76:79], v42 offset:24384
	ds_read2st64_b64 v[80:83], v43 offset0:38 offset1:39
	ds_read2st64_b64 v[84:87], v43 offset0:40 offset1:41
	ds_read_b128 v[100:103], v42 offset:24448
	ds_read_b128 v[104:107], v42 offset:24512
	ds_read_b64 v[108:109], v1 offset:23808
	ds_read_b128 v[112:115], v0 offset:24832
	v_mov_b32_e32 v110, v3
	v_mov_b32_e32 v111, v3
	v_mov_b32_e32 v2, v3
	v_cvt_pk_bf16_f32 v116, v16, v17
	s_waitcnt lgkmcnt(0)
	v_cvt_pk_bf16_f32 v0, v112, v113
	v_cvt_pk_bf16_f32 v1, v114, v115
	v_cvt_pk_bf16_f32 v117, v18, v19
	v_cvt_pk_bf16_f32 v118, v4, v5
	v_mfma_f32_16x16x32_bf16 v[108:111], v[108:111], v[0:3], 0
	v_cvt_pk_bf16_f32 v119, v6, v7
	v_cvt_pk_bf16_f32 v112, v8, v9
	v_cvt_pk_bf16_f32 v113, v10, v11
	v_mfma_f32_16x16x32_bf16 v[38:41], v[38:41], v[116:119], v[108:111]
	v_cvt_pk_bf16_f32 v114, v28, v29
	v_cvt_pk_bf16_f32 v115, v30, v31
	v_pk_mul_f32 v[6:7], v[6:7], v[78:79]
	s_nop 0
	v_cvt_pk_bf16_f32 v108, v12, v13
	v_mfma_f32_16x16x32_bf16 v[38:41], v[60:63], v[112:115], v[38:41]
	v_cvt_pk_bf16_f32 v109, v14, v15
	v_cvt_pk_bf16_f32 v110, v20, v21
	v_cvt_pk_bf16_f32 v111, v22, v23
	v_pk_mul_f32 v[4:5], v[4:5], v[76:77]
	v_cvt_pk_bf16_f32 v60, v32, v33
	v_mfma_f32_16x16x32_bf16 v[38:41], v[64:67], v[108:111], v[38:41]
	v_mov_b32_e32 v64, v82
	v_mov_b32_e32 v65, v83
	v_mov_b32_e32 v66, v3
	v_mov_b32_e32 v67, v3
	v_cvt_pk_bf16_f32 v61, v34, v35
	v_cvt_pk_bf16_f32 v62, v24, v25
	v_cvt_pk_bf16_f32 v63, v26, v27
	v_mfma_f32_16x16x32_bf16 v[4:7], v[64:67], v[0:3], v[4:7]
	v_mov_b32_e32 v64, v84
	v_mov_b32_e32 v65, v85
	v_pk_mul_f32 v[10:11], v[10:11], v[102:103]
	v_mfma_f32_16x16x32_bf16 v[38:41], v[68:71], v[60:63], v[38:41]
	v_mov_b32_e32 v60, v80
	v_mov_b32_e32 v61, v81
	v_mov_b32_e32 v62, v3
	v_mov_b32_e32 v63, v3
	v_pk_mul_f32 v[8:9], v[8:9], v[100:101]
	v_pk_mul_f32 v[18:19], v[18:19], v[74:75]
	v_pk_mul_f32 v[16:17], v[16:17], v[72:73]
	v_mfma_f32_16x16x32_bf16 v[8:11], v[64:67], v[0:3], v[8:11]
	v_mov_b32_e32 v64, v86
	v_mov_b32_e32 v65, v87
	v_pk_mul_f32 v[30:31], v[30:31], v[106:107]
	v_mfma_f32_16x16x32_bf16 v[16:19], v[60:63], v[0:3], v[16:19]
	ds_read_b128 v[60:63], v42 offset:24576
	ds_read2st64_b64 v[68:71], v43 offset0:42 offset1:43
	ds_read2st64_b64 v[72:75], v43 offset0:44 offset1:45
	v_pk_mul_f32 v[28:29], v[28:29], v[104:105]
	v_mov_b32_e32 v78, v3
	v_mov_b32_e32 v79, v3
	s_waitcnt lgkmcnt(1)
	v_mov_b32_e32 v76, v68
	v_mov_b32_e32 v77, v69
	v_mfma_f32_16x16x32_bf16 v[28:31], v[64:67], v[0:3], v[28:31]
	ds_read_b128 v[64:67], v42 offset:24640
	v_pk_mul_f32 v[14:15], v[14:15], v[62:63]
	v_pk_mul_f32 v[12:13], v[12:13], v[60:61]
	v_mov_b32_e32 v60, v70
	v_mov_b32_e32 v61, v71
	v_mov_b32_e32 v62, v3
	v_mov_b32_e32 v63, v3
	s_sub_i32 s15, s8, 64
	v_mfma_f32_16x16x32_bf16 v[12:15], v[76:79], v[0:3], v[12:15]
	ds_read_b128 v[68:71], v42 offset:24704
	ds_read_b128 v[76:79], v42 offset:24768
	s_waitcnt lgkmcnt(2)
	v_pk_mul_f32 v[22:23], v[22:23], v[66:67]
	v_pk_mul_f32 v[20:21], v[20:21], v[64:65]
	s_cmp_lt_u32 s9, 16
	v_mov_b32_e32 v64, v74
	v_mfma_f32_16x16x32_bf16 v[20:23], v[60:63], v[0:3], v[20:23]
	v_mov_b32_e32 v60, v72
	v_mov_b32_e32 v61, v73
	v_mov_b32_e32 v65, v75
	v_mov_b32_e32 v66, v3
	v_mov_b32_e32 v67, v3
	s_cselect_b32 s18, 0xf0, s93
	s_add_i32 s20, s18, s14
	s_and_b64 s[18:19], vcc, exec
	s_waitcnt lgkmcnt(1)
	v_pk_mul_f32 v[34:35], v[34:35], v[70:71]
	v_pk_mul_f32 v[32:33], v[32:33], v[68:69]
	s_waitcnt lgkmcnt(0)
	v_pk_mul_f32 v[26:27], v[26:27], v[78:79]
	v_pk_mul_f32 v[24:25], v[24:25], v[76:77]
	s_cselect_b32 s15, s15, s20
	v_mfma_f32_16x16x32_bf16 v[32:35], v[60:63], v[0:3], v[32:35]
	s_or_b32 s15, s15, 15
	v_cvt_pk_bf16_f32 v38, v38, s0
	v_mfma_f32_16x16x32_bf16 v[24:27], v[64:67], v[0:3], v[24:27]
	v_add_u32_e32 v2, s8, v45
	v_sub_u32_e32 v0, s15, v45
	v_subrev_u32_e32 v1, 64, v2
	v_cndmask_b32_e32 v0, v0, v1, vcc
	v_ashrrev_i32_e32 v1, 31, v0
	v_lshl_add_u64 v[0:1], s[16:17], 0, v[0:1]
	v_lshlrev_b64 v[0:1], 11, v[0:1]
	v_lshl_add_u64 v[0:1], v[36:37], 0, v[0:1]
	global_store_short v[0:1], v38, off
	s_and_b64 s[18:19], vcc, exec
	s_mov_b32 s18, 0xfffff800
	s_cselect_b32 s18, 0x800, s18
	s_cselect_b32 s19, 0, -1
	v_cvt_pk_bf16_f32 v38, v39, s0
	v_lshl_add_u64 v[0:1], v[0:1], 0, s[18:19]
	global_store_short v[0:1], v38, off
	v_cvt_pk_bf16_f32 v38, v40, s0
	v_lshl_add_u64 v[0:1], v[0:1], 0, s[18:19]
	global_store_short v[0:1], v38, off
	v_cvt_pk_bf16_f32 v2, v41, s0
	v_lshl_add_u64 v[0:1], v[0:1], 0, s[18:19]
	global_store_short v[0:1], v2, off
	s_branch .LBB0_778

; __device__ __forceinline__ void scan_phase(const Params& P, int l, LAS unsigned char* lds) {
;     ...
;                 if (it >= 0) {
;                     const LAS unsigned char* sl = lds + (it & 1) * SLOT;
;                     const int n0 = it * TS; const int plo = dir ? (n0 < 256 ? 256 - TS - n0 : TPB + 256 - TS - n0) : n0;
;                     u32x4 fw[4], fq[4]; u32x2 fk[8];
; #pragma unroll
;                     for (int j = 0; j < 4; ++j) { fw[j] = *(const LAS u32x4*)(sl + (j * 64 + lane) * 16); fq[j] = *(const LAS u32x4*)(sl + 4096 + (j * 64 + lane) * 16); }
; #pragma unroll
;                     for (int m = 0; m < 8; ++m) fk[m] = *(const LAS u32x2*)(sl + 8192 + (m * 64 + lane) * 8);
;                     const u32x2 fa = *(const LAS u32x2*)(sl + 12288 + lane * 8), ft = *(const LAS u32x2*)(sl + 12800 + lane * 8);
;                     const f32x4 b4 = *(const LAS f32x4*)(sl + 13312 + lane * 16), v4 = *(const LAS f32x4*)(sl + 14336 + lane * 16);
;                     const float egC = *(const LAS float*)(sl + 15360);
;                     bf16x8 sf[4];
; #pragma unroll
;                     for (int j = 0; j < 4; ++j) sf[j] = __builtin_bit_cast(bf16x8, (u32x4){pk2n(St[2 * j][0], St[2 * j][1]), pk2n(St[2 * j][2], St[2 * j][3]), pk2n(St[2 * j + 1][0], St[2 * j + 1][1]), pk2n(St[2 * j + 1][2], St[2 * j + 1][3])});
;                     const bf16x8 bv = __builtin_bit_cast(bf16x8, (u32x4){pk2n(b4[0] * v4[0], b4[1] * v4[1]), pk2n(b4[2] * v4[2], b4[3] * v4[3]), 0u, 0u});
;                     const bf16x8 FT8 = __builtin_bit_cast(bf16x8, (u32x4){ft[0], ft[1], 0u, 0u}), FA8 = __builtin_bit_cast(bf16x8, (u32x4){fa[0], fa[1], 0u, 0u});
;                     const f32x4 U = __builtin_amdgcn_mfma_f32_16x16x32_bf16(FT8, bv, zero4, 0, 0, 0);
;                     f32x4 Pw = zero4, O = zero4;
; #pragma unroll
;                     for (int j = 0; j < 4; ++j) { Pw = __builtin_amdgcn_mfma_f32_16x16x32_bf16(__builtin_bit_cast(bf16x8, fw[j]), sf[j], Pw, 0, 0, 0);
;                         O = __builtin_amdgcn_mfma_f32_16x16x32_bf16(__builtin_bit_cast(bf16x8, fq[j]), sf[j], O, 0, 0, 0); }
;                     const f32x4 Vn = U - Pw;
;                     const bf16x8 vn8 = __builtin_bit_cast(bf16x8, (u32x4){pk2n(Vn[0], Vn[1]), pk2n(Vn[2], Vn[3]), 0u, 0u});
;                     O = __builtin_amdgcn_mfma_f32_16x16x32_bf16(FA8, vn8, O, 0, 0, 0);
; #pragma unroll
.LBB0_785:
	s_cmp_lt_i32 s9, 0
	s_cbranch_scc1 .LBB0_784
	s_bitcmp1_b32 s9, 0
	s_cselect_b32 s15, 0x6500, 0
	s_add_i32 s19, s15, 0
	v_add_u32_e32 v0, s19, v46
	ds_read_b128 v[38:41], v0
	ds_read_b128 v[60:63], v0 offset:1024
	ds_read_b128 v[64:67], v0 offset:4096
	ds_read_b128 v[68:71], v0 offset:5120
	ds_read_b128 v[72:75], v0 offset:2048
	ds_read_b128 v[76:79], v0 offset:3072
	ds_read_b128 v[80:83], v0 offset:6144
	ds_read_b128 v[84:87], v0 offset:7168
	v_cvt_pk_bf16_f32 v120, v4, v5
	v_cvt_pk_bf16_f32 v121, v6, v7
	v_cvt_pk_bf16_f32 v122, v8, v9
	v_cvt_pk_bf16_f32 v123, v10, v11
	v_add_u32_e32 v1, s19, v48
	ds_read2st64_b64 v[100:103], v1 offset0:16 offset1:17
	ds_read2st64_b64 v[104:107], v1 offset0:18 offset1:19
	ds_read2st64_b64 v[108:111], v1 offset0:20 offset1:21
	ds_read2st64_b64 v[112:115], v1 offset0:22 offset1:23
	ds_read2st64_b64 v[116:119], v1 offset0:24 offset1:25
	s_waitcnt lgkmcnt(12)
	v_mfma_f32_16x16x32_bf16 v[38:41], v[38:41], v[120:123], 0
	v_cvt_pk_bf16_f32 v132, v16, v17
	v_cvt_pk_bf16_f32 v133, v18, v19
	v_cvt_pk_bf16_f32 v134, v12, v13
	s_waitcnt lgkmcnt(10)
	v_mfma_f32_16x16x32_bf16 v[64:67], v[64:67], v[120:123], 0
	v_cvt_pk_bf16_f32 v135, v14, v15
	ds_read_b128 v[124:127], v0 offset:13312
	ds_read_b128 v[128:131], v0 offset:14336
	v_mov_b32_e32 v0, s19
	v_mfma_f32_16x16x32_bf16 v[38:41], v[60:63], v[132:135], v[38:41]
	v_cvt_pk_bf16_f32 v60, v24, v25
	v_cvt_pk_bf16_f32 v61, v26, v27
	v_cvt_pk_bf16_f32 v62, v20, v21
	s_waitcnt lgkmcnt(11)
	v_mfma_f32_16x16x32_bf16 v[64:67], v[68:71], v[132:135], v[64:67]
	v_cvt_pk_bf16_f32 v63, v22, v23
	ds_read_b32 v42, v0 offset:15360
	s_waitcnt lgkmcnt(1)
	v_pk_mul_f32 v[0:1], v[124:125], v[128:129]
	v_mfma_f32_16x16x32_bf16 v[38:41], v[72:75], v[60:63], v[38:41]
	v_mul_f32_e64 v72, v126, v130
	v_mul_f32_e64 v73, v127, v131
	v_cvt_pk_bf16_f32 v68, v32, v33
	v_cvt_pk_bf16_f32 v69, v34, v35
	v_mfma_f32_16x16x32_bf16 v[60:63], v[80:83], v[60:63], v[64:67]
	v_cvt_pk_bf16_f32 v70, v28, v29
	v_cvt_pk_bf16_f32 v71, v30, v31
	v_cvt_pk_bf16_f32 v0, v0, v1
	v_mov_b32_e32 v64, v118
	v_mov_b32_e32 v65, v119
	v_mov_b32_e32 v66, v3
	v_mov_b32_e32 v67, v3
	v_cvt_pk_bf16_f32 v1, v72, v73
	v_mov_b32_e32 v2, v3
	v_mfma_f32_16x16x32_bf16 v[38:41], v[76:79], v[68:71], v[38:41]
	s_waitcnt lgkmcnt(0)
	v_pk_mul_f32 v[6:7], v[6:7], v[42:43] op_sel_hi:[1,0]
	v_pk_mul_f32 v[4:5], v[4:5], v[42:43] op_sel_hi:[1,0]
	v_pk_mul_f32 v[10:11], v[10:11], v[42:43] op_sel_hi:[1,0]
	v_mfma_f32_16x16x32_bf16 v[64:67], v[64:67], v[0:3], 0
	v_mul_f32_e64 v8, v8, v42
	v_mul_f32_e64 v9, v9, v42
	v_pk_mul_f32 v[18:19], v[18:19], v[42:43] op_sel_hi:[1,0]
	v_pk_mul_f32 v[16:17], v[16:17], v[42:43] op_sel_hi:[1,0]
	v_pk_mul_f32 v[14:15], v[14:15], v[42:43] op_sel_hi:[1,0]
	v_pk_mul_f32 v[12:13], v[12:13], v[42:43] op_sel_hi:[1,0]
	s_nop 1
	v_sub_f32_e32 v0, v65, v39
	v_sub_f32_e32 v38, v64, v38
	v_sub_f32_e32 v1, v67, v41
	v_sub_f32_e32 v2, v66, v40
	v_cvt_pk_bf16_f32 v0, v38, v0
	v_mov_b32_e32 v38, v100
	v_mov_b32_e32 v39, v101
	v_mov_b32_e32 v40, v3
	v_mov_b32_e32 v41, v3
	v_mov_b32_e32 v64, v102
	v_mov_b32_e32 v65, v103
	v_mov_b32_e32 v66, v3
	v_mov_b32_e32 v67, v3
	v_cvt_pk_bf16_f32 v1, v2, v1
	v_mov_b32_e32 v2, v3
	s_sub_i32 s15, s8, 64
	v_pk_mul_f32 v[26:27], v[26:27], v[42:43] op_sel_hi:[1,0]
	v_mfma_f32_16x16x32_bf16 v[4:7], v[38:41], v[0:3], v[4:7]
	v_mov_b32_e32 v38, v104
	v_mov_b32_e32 v39, v105
	v_pk_mul_f32 v[24:25], v[24:25], v[42:43] op_sel_hi:[1,0]
	v_mfma_f32_16x16x32_bf16 v[8:11], v[64:67], v[0:3], v[8:11]
	v_mov_b32_e32 v64, v106
	v_mov_b32_e32 v65, v107
	v_pk_mul_f32 v[22:23], v[22:23], v[42:43] op_sel_hi:[1,0]
	v_mfma_f32_16x16x32_bf16 v[16:19], v[38:41], v[0:3], v[16:19]
	v_mov_b32_e32 v38, v108
	v_mov_b32_e32 v39, v109
	v_pk_mul_f32 v[20:21], v[20:21], v[42:43] op_sel_hi:[1,0]
	v_mfma_f32_16x16x32_bf16 v[12:15], v[64:67], v[0:3], v[12:15]
	v_mov_b32_e32 v64, v110
	v_mov_b32_e32 v65, v111
	s_cmp_lt_u32 s9, 16
	v_mfma_f32_16x16x32_bf16 v[24:27], v[38:41], v[0:3], v[24:27]
	v_mov_b32_e32 v118, v3
	v_mov_b32_e32 v38, v112
	v_mov_b32_e32 v39, v113
	v_mfma_f32_16x16x32_bf16 v[20:23], v[64:67], v[0:3], v[20:23]
	v_mov_b32_e32 v64, v114
	v_mov_b32_e32 v65, v115
	v_mov_b32_e32 v119, v3
	s_cselect_b32 s18, 0xf0, s93
	v_mfma_f32_16x16x32_bf16 v[60:63], v[84:87], v[68:71], v[60:63]
	s_add_i32 s20, s18, s14
	s_and_b64 s[18:19], vcc, exec
	v_pk_mul_f32 v[34:35], v[34:35], v[42:43] op_sel_hi:[1,0]
	v_pk_mul_f32 v[32:33], v[32:33], v[42:43] op_sel_hi:[1,0]
	v_pk_mul_f32 v[30:31], v[30:31], v[42:43] op_sel_hi:[1,0]
	v_pk_mul_f32 v[28:29], v[28:29], v[42:43] op_sel_hi:[1,0]
	s_cselect_b32 s15, s15, s20
	v_mfma_f32_16x16x32_bf16 v[32:35], v[38:41], v[0:3], v[32:35]
	s_or_b32 s15, s15, 15
	v_mfma_f32_16x16x32_bf16 v[28:31], v[64:67], v[0:3], v[28:31]
	v_mfma_f32_16x16x32_bf16 v[38:41], v[116:119], v[0:3], v[60:63]
	v_add_u32_e32 v2, s8, v45
	v_sub_u32_e32 v0, s15, v45
	v_subrev_u32_e32 v1, 64, v2
	v_cndmask_b32_e32 v0, v0, v1, vcc
	v_ashrrev_i32_e32 v1, 31, v0
	v_lshl_add_u64 v[0:1], s[16:17], 0, v[0:1]
	v_lshlrev_b64 v[0:1], 11, v[0:1]
	s_nop 0
	v_cvt_pk_bf16_f32 v38, v38, s0
	v_lshl_add_u64 v[0:1], v[36:37], 0, v[0:1]
	global_store_short v[0:1], v38, off
	s_and_b64 s[18:19], vcc, exec
	s_mov_b32 s18, 0xfffff800
	s_cselect_b32 s18, 0x800, s18
	s_cselect_b32 s19, 0, -1
	v_cvt_pk_bf16_f32 v38, v39, s0
	v_lshl_add_u64 v[0:1], v[0:1], 0, s[18:19]
	global_store_short v[0:1], v38, off
	v_cvt_pk_bf16_f32 v38, v40, s0
	v_lshl_add_u64 v[0:1], v[0:1], 0, s[18:19]
	global_store_short v[0:1], v38, off
	v_cvt_pk_bf16_f32 v2, v41, s0
	v_lshl_add_u64 v[0:1], v[0:1], 0, s[18:19]
	global_store_short v[0:1], v2, off
	s_branch .LBB0_784
